# grid barrier between final sample reduce and final LayerNorm replaced by per-wave drain + L1 invalidate (dependency is wave-local)
# speedup vs baseline: 1.0302x; 1.0001x over previous
; __device__ __forceinline__ unsigned xb_ld(unsigned* p)              { return __hip_atomic_load(p, __ATOMIC_RELAXED, __HIP_MEMORY_SCOPE_AGENT); }
; __device__ __forceinline__ unsigned xb_add(unsigned* p, unsigned v) { return __hip_atomic_fetch_add(p, v, __ATOMIC_RELAXED, __HIP_MEMORY_SCOPE_AGENT); }
; #define XB_SPIN(cond, bar) do { unsigned _sp = 0; while (cond) { __builtin_amdgcn_s_sleep(1); \
;     if ((++_sp & 255u) == 0u) { if (xb_ld(&(bar)[XB_TMO])) break; if (_sp > XB_SPIN_CAP) { atomicAdd(&(bar)[XB_TMO], 1u); break; } } } } while (0)
; #define CASE(k) if (PH_ON(k) && ph_lo <= (k) && (k) < ph_hi)
; #define SEAM(k) if (ph_lo <= (k) && (k) < ph_hi && ph_hi - ph_lo > 1) xcd_barrier(bar);
; __device__ __forceinline__ void xcd_barrier(const XcdBarrier& b) {
;     asm volatile("s_waitcnt vmcnt(0)" ::: "memory");
;     __syncthreads();
;     if (threadIdx.x == 0) {
;         unsigned* bar = b.bar;
;         __builtin_amdgcn_s_waitcnt(0);
;         unsigned nloc = b.st[0], nx = b.st[1];
;         if (nloc == 0u) { xcd_barrier_complete(bar, b.x, nloc, nx); b.st[0] = nloc; b.st[1] = nx; }
;         const unsigned old = xb_add(&bar[XB_XSUB(b.x)], 1u);
;         const unsigned gen = old / nloc;
;         if (old + 1u == (gen + 1u) * nloc) {
;             __builtin_amdgcn_fence(__ATOMIC_RELEASE, "agent");
;             asm volatile("s_waitcnt vmcnt(0)" ::: "memory");
;             const unsigned og = xb_add(&bar[XB_TOP], 1u);
;             const unsigned tg = og / nx;
;             if (og + 1u == (tg + 1u) * nx) xb_add(&bar[XB_TOPGEN], 1u);
;             else XB_SPIN(xb_ld(&bar[XB_TOPGEN]) == tg, bar);
;             __builtin_amdgcn_fence(__ATOMIC_ACQUIRE, "agent");
;             xb_add(&bar[XB_XGEN(b.x)], 1u);
;             asm volatile("s_waitcnt vmcnt(0)" ::: "memory");
;         } else {
;             XB_SPIN(xb_ld(&bar[XB_XGEN(b.x)]) == gen, bar);
;             __builtin_amdgcn_fence(__ATOMIC_ACQUIRE, "agent");
;             asm volatile("s_waitcnt vmcnt(0)" ::: "memory");
;         }
;     }
;     __syncthreads();
; }
; __global__ void __launch_bounds__(512, 2) mega(Params p) {
;     ...
;         CASE(16) sample_reduce<0>((const float*)(ws + O_SLAB), 11, nullptr, nullptr, 0.5f, (const float*)(ws + O_ST3), p.in[28], p.in[29], XB, nullptr, nullptr, nullptr, XB); SEAM(16)
;         CASE(14) phase_ln(XB, p.out + OUT_Y, nullptr, p.in[32], p.in[33]);
.LBB0_1721:
	s_or_b64 exec, exec, s[12:13]
	v_readlane_b32 s0, v252, 12
	v_readlane_b32 s1, v252, 13
	s_andn2_b64 vcc, exec, s[0:1]
	s_cbranch_vccnz .LBB0_1767
	s_waitcnt vmcnt(0)
	buffer_inv sc1
	s_waitcnt vmcnt(0)
	s_branch .LBB0_1767
	s_waitcnt vmcnt(0)
	s_waitcnt lgkmcnt(0)
	s_barrier
	s_mov_b64 s[36:37], exec
	v_readlane_b32 s0, v252, 6
	v_readlane_b32 s1, v252, 7
	s_and_b64 s[0:1], s[36:37], s[0:1]
	s_mov_b64 exec, s[0:1]
	s_cbranch_execz .LBB0_1766
	s_add_i32 s0, 0, 0x23f10
	v_mov_b32_e32 v0, s0
	s_waitcnt vmcnt(0) expcnt(0) lgkmcnt(0)
	ds_read_b32 v2, v0
	s_add_i32 s0, 0, 0x23f14
	v_mov_b32_e32 v0, s0
	ds_read_b32 v0, v0
	s_waitcnt lgkmcnt(1)
	v_cmp_ne_u32_e32 vcc, 0, v2
	s_cbranch_vccnz .LBB0_1737
	s_add_u32 s4, s52, 0x2fb43200
	s_addc_u32 s5, s53, 0
	s_add_u32 s8, s52, 0x2fb43400
	s_addc_u32 s9, s53, 0
	s_add_u32 s10, s52, 0x2fb43500
	s_addc_u32 s11, s53, 0
	s_add_u32 s12, s52, 0x2fb43600
	s_addc_u32 s13, s53, 0
	s_add_u32 s14, s52, 0x2fb43700
	s_addc_u32 s15, s53, 0
	s_add_u32 s16, s52, 0x2fb43800
	s_addc_u32 s17, s53, 0
	s_add_u32 s18, s52, 0x2fb43900
	s_addc_u32 s19, s53, 0
	s_add_u32 s20, s52, 0x2fb43a00
	s_addc_u32 s21, s53, 0
	s_add_u32 s22, s52, 0x2fb43b00
	s_addc_u32 s23, s53, 0
	s_add_u32 s24, s52, 0x2fb43c00
	s_addc_u32 s25, s53, 0
	s_add_u32 s26, s52, 0x2fb43d00
	s_addc_u32 s27, s53, 0
	s_add_u32 s28, s52, 0x2fb43e00
	s_addc_u32 s29, s53, 0
	s_add_u32 s30, s52, 0x2fb43f00
	s_addc_u32 s31, s53, 0
	s_add_u32 s34, s52, 0x2fb44000
	s_addc_u32 s35, s53, 0
	s_add_u32 s38, s52, 0x2fb44100
	s_addc_u32 s39, s53, 0
	s_add_u32 s40, s52, 0x2fb44200
	s_addc_u32 s41, s53, 0
	v_readlane_b32 s0, v252, 0
	s_add_u32 s42, s52, 0x2fb44300
	s_mul_i32 s0, s83, s0
	s_addc_u32 s43, s53, 0
	s_mul_i32 s0, s0, s82
	s_mov_b32 s1, 1
	s_mov_b64 s[6:7], 0
	s_waitcnt lgkmcnt(0)
	v_mov_b64_e32 v[0:1], s[8:9]
	v_mov_b64_e32 v[2:3], s[10:11]
	v_mov_b64_e32 v[4:5], s[12:13]
	v_mov_b64_e32 v[6:7], s[14:15]
	v_mov_b64_e32 v[8:9], s[16:17]
	v_mov_b64_e32 v[10:11], s[18:19]
	v_mov_b64_e32 v[12:13], s[20:21]
	v_mov_b64_e32 v[14:15], s[22:23]
	v_mov_b64_e32 v[16:17], s[24:25]
	v_mov_b64_e32 v[18:19], s[26:27]
	v_mov_b64_e32 v[20:21], s[28:29]
	v_mov_b64_e32 v[22:23], s[30:31]
	v_mov_b64_e32 v[24:25], s[34:35]
	v_mov_b64_e32 v[26:27], s[38:39]
	v_mov_b64_e32 v[28:29], s[40:41]
	v_mov_b64_e32 v[30:31], s[42:43]
	s_branch .LBB0_1727
